# weight-conversion tile loads issued together; first-barrier counter loads issued together
# speedup vs baseline: 1.0138x; 1.0138x over previous
.LBB0_108:
	s_mov_b64 s[52:53], -1
	s_mov_b64 s[46:47], 0
	s_andn2_b64 vcc, exec, s[26:27]
	s_mov_b64 s[50:51], 0
	s_mov_b64 s[54:55], 0
	s_cbranch_vccnz .LBB0_111
	s_mov_b64 s[54:55], -1
	s_mov_b64 s[52:53], 0
	s_cmpk_lt_i32 s7, 0x400
	s_cbranch_scc0 .LBB0_111
	s_and_b32 s48, s7, 0xffffffc0
	s_lshl_b32 s8, s7, 6
	s_and_b32 s44, s8, 0xfc0
	v_add_u32_e32 v12, s48, v30
	s_lshl_b32 s92, s44, 2
	v_ashrrev_i32_e32 v13, 31, v12
	v_lshl_add_u64 v[16:17], v[4:5], 0, s[92:93]
	v_lshlrev_b64 v[12:13], 14, v[12:13]
	v_lshl_add_u64 v[12:13], v[16:17], 0, v[12:13]
	s_waitcnt lgkmcnt(0)
	s_barrier
	global_load_dwordx4 v[12:15], v[12:13], off
	v_add_u32_e32 v200, s48, v32
	v_ashrrev_i32_e32 v201, 31, v200
	v_lshlrev_b64 v[200:201], 14, v[200:201]
	v_lshl_add_u64 v[200:201], v[16:17], 0, v[200:201]
	global_load_dwordx4 v[208:211], v[200:201], off
	v_add_u32_e32 v202, s48, v33
	v_ashrrev_i32_e32 v203, 31, v202
	v_lshlrev_b64 v[202:203], 14, v[202:203]
	v_lshl_add_u64 v[202:203], v[16:17], 0, v[202:203]
	global_load_dwordx4 v[212:215], v[202:203], off
	v_add_u32_e32 v204, s48, v34
	v_ashrrev_i32_e32 v205, 31, v204
	v_lshlrev_b64 v[204:205], 14, v[204:205]
	v_lshl_add_u64 v[204:205], v[16:17], 0, v[204:205]
	global_load_dwordx4 v[216:219], v[204:205], off
	v_add_u32_e32 v0, v2, v31
	v_add_u32_e32 v11, 0x1040, v0
	s_ashr_i32 s49, s48, 31
	s_lshl_b64 s[8:9], s[48:49], 1
	s_movk_i32 s82, 0x1bff
	s_mov_b64 s[54:55], 0
	s_mov_b64 s[50:51], -1
	s_waitcnt vmcnt(3)
	ds_write2_b32 v0, v12, v13 offset1:1
	ds_write2_b32 v0, v14, v15 offset0:2 offset1:3
	s_waitcnt vmcnt(2)
	ds_write2_b32 v11, v208, v209 offset1:1
	v_add_u32_e32 v11, 0x1048, v0
	ds_write2_b32 v11, v210, v211 offset1:1
	v_add_u32_e32 v11, 0x2080, v0
	s_waitcnt vmcnt(1)
	ds_write2_b32 v11, v212, v213 offset1:1
	v_add_u32_e32 v11, 0x2088, v0
	ds_write2_b32 v11, v214, v215 offset1:1
	s_add_u32 s48, s0, s8
	v_add_u32_e32 v11, 0x30c0, v0
	v_add_u32_e32 v0, 0x30c8, v0
	s_addc_u32 s49, s1, s9
	s_waitcnt vmcnt(0)
	ds_write2_b32 v11, v216, v217 offset1:1
	ds_write2_b32 v0, v218, v219 offset1:1
	s_waitcnt lgkmcnt(0)
	s_barrier

.LBB0_117:
	v_add_u32_e32 v44, v2, v31
	s_and_b64 vcc, exec, s[54:55]
	v_add_u32_e32 v42, 0x1040, v44
	v_add_u32_e32 v43, 0x1048, v44
	v_add_u32_e32 v40, 0x2080, v44
	v_add_u32_e32 v41, 0x2088, v44
	v_add_u32_e32 v11, 0x30c0, v44
	v_add_u32_e32 v39, 0x30c8, v44
	s_cbranch_vccz .LBB0_119
	s_add_i32 s8, s8, s7
	s_lshl_b32 s9, s8, 2
	s_and_b32 s9, s9, 0x7fffffc0
	s_lshl_b32 s8, s8, 6
	s_and_b32 s44, s8, 0x3c0
	v_add_u32_e32 v12, s9, v30
	s_lshl_b32 s92, s44, 2
	v_ashrrev_i32_e32 v13, 31, v12
	v_lshl_add_u64 v[16:17], v[6:7], 0, s[92:93]
	v_lshlrev_b64 v[12:13], 12, v[12:13]
	v_lshl_add_u64 v[12:13], v[16:17], 0, v[12:13]
	s_waitcnt lgkmcnt(0)
	s_barrier
	global_load_dwordx4 v[12:15], v[12:13], off
	v_add_u32_e32 v200, s9, v32
	v_ashrrev_i32_e32 v201, 31, v200
	v_lshlrev_b64 v[200:201], 12, v[200:201]
	v_lshl_add_u64 v[200:201], v[16:17], 0, v[200:201]
	global_load_dwordx4 v[208:211], v[200:201], off
	v_add_u32_e32 v202, s9, v33
	v_ashrrev_i32_e32 v203, 31, v202
	v_lshlrev_b64 v[202:203], 12, v[202:203]
	v_lshl_add_u64 v[202:203], v[16:17], 0, v[202:203]
	global_load_dwordx4 v[212:215], v[202:203], off
	v_add_u32_e32 v204, s9, v34
	v_ashrrev_i32_e32 v205, 31, v204
	v_lshlrev_b64 v[204:205], 12, v[204:205]
	v_lshl_add_u64 v[204:205], v[16:17], 0, v[204:205]
	global_load_dwordx4 v[216:219], v[204:205], off
	s_lshl_b32 s8, s9, 1
	s_add_u32 s48, s5, s8
	s_movk_i32 s82, 0x1bff
	s_addc_u32 s49, s6, 0
	s_mov_b64 s[52:53], 0
	s_mov_b64 s[50:51], -1
	s_waitcnt vmcnt(3)
	ds_write2_b32 v44, v12, v13 offset1:1
	ds_write2_b32 v44, v14, v15 offset0:2 offset1:3
	s_waitcnt vmcnt(2)
	ds_write2_b32 v42, v208, v209 offset1:1
	ds_write2_b32 v43, v210, v211 offset1:1
	s_waitcnt vmcnt(1)
	ds_write2_b32 v40, v212, v213 offset1:1
	ds_write2_b32 v41, v214, v215 offset1:1
	s_waitcnt vmcnt(0)
	ds_write2_b32 v11, v216, v217 offset1:1
	ds_write2_b32 v39, v218, v219 offset1:1
	s_waitcnt lgkmcnt(0)
	s_barrier

.LBB0_141:
	s_mul_hi_i32 s8, s7, 0x2aaaaaab
	s_lshr_b32 s9, s8, 31
	s_ashr_i32 s8, s8, 3
	s_add_i32 s9, s8, s9
	s_lshl_b32 s8, s9, 6
	s_mul_i32 s9, s9, 48
	s_sub_i32 s9, s7, s9
	s_lshl_b32 s44, s9, 6
	s_ashr_i32 s45, s44, 31
	v_lshl_add_u64 v[16:17], s[44:45], 2, v[8:9]
	v_add_u32_e32 v0, s8, v30
	v_mad_i64_i32 v[12:13], s[10:11], v0, s33, v[16:17]
	s_waitcnt lgkmcnt(0)
	s_barrier
	global_load_dwordx4 v[12:15], v[12:13], off
	v_add_u32_e32 v206, s8, v32
	v_mad_i64_i32 v[200:201], s[10:11], v206, s33, v[16:17]
	global_load_dwordx4 v[208:211], v[200:201], off
	v_add_u32_e32 v206, s8, v33
	v_mad_i64_i32 v[202:203], s[10:11], v206, s33, v[16:17]
	global_load_dwordx4 v[212:215], v[202:203], off
	v_add_u32_e32 v206, s8, v34
	v_mad_i64_i32 v[204:205], s[10:11], v206, s33, v[16:17]
	global_load_dwordx4 v[216:219], v[204:205], off
	s_ashr_i32 s9, s8, 31
	s_waitcnt vmcnt(3)
	ds_write2_b32 v44, v12, v13 offset1:1
	ds_write2_b32 v44, v14, v15 offset0:2 offset1:3
	s_waitcnt vmcnt(2)
	ds_write2_b32 v42, v208, v209 offset1:1
	ds_write2_b32 v43, v210, v211 offset1:1
	s_lshl_b64 s[8:9], s[8:9], 1
	s_add_u32 s48, s0, s8
	s_addc_u32 s49, s1, s9
	s_waitcnt vmcnt(1)
	ds_write2_b32 v40, v212, v213 offset1:1
	ds_write2_b32 v41, v214, v215 offset1:1
	s_waitcnt vmcnt(0)
	ds_write2_b32 v11, v216, v217 offset1:1
	ds_write2_b32 v39, v218, v219 offset1:1
	s_waitcnt lgkmcnt(0)
	s_barrier

.LBB0_292:
	s_andn2_b64 vcc, exec, s[24:25]
	s_mov_b64 s[24:25], s[22:23]
	s_cbranch_vccnz .LBB0_322
	s_add_i32 s5, s20, 0xfffffe80
	s_cmpk_gt_u32 s5, 0x2ff
	s_waitcnt lgkmcnt(0)
	s_barrier
	s_cbranch_scc0 .LBB0_296
	s_cmpk_gt_u32 s5, 0x30f
	s_cbranch_scc0 .LBB0_297
	s_add_i32 s4, s20, 0xfffffb70
	s_lshl_b32 s6, s4, 2
	s_and_b32 s6, s6, 0x7fffffc0
	s_lshl_b32 s4, s4, 6
	s_and_b32 s4, s4, 0x3c0
	v_add_u32_e32 v2, s6, v35
	s_lshl_b32 s92, s4, 2
	v_ashrrev_i32_e32 v3, 31, v2
	v_lshl_add_u64 v[6:7], v[40:41], 0, s[92:93]
	v_lshlrev_b64 v[2:3], 12, v[2:3]
	v_lshl_add_u64 v[2:3], v[6:7], 0, v[2:3]
	s_barrier
	global_load_dwordx4 v[2:5], v[2:3], off
	v_add_u32_e32 v206, s6, v158
	v_ashrrev_i32_e32 v207, 31, v206
	v_lshlrev_b64 v[206:207], 12, v[206:207]
	v_lshl_add_u64 v[206:207], v[6:7], 0, v[206:207]
	global_load_dwordx4 v[212:215], v[206:207], off
	v_add_u32_e32 v208, s6, v159
	v_ashrrev_i32_e32 v209, 31, v208
	v_lshlrev_b64 v[208:209], 12, v[208:209]
	v_lshl_add_u64 v[208:209], v[6:7], 0, v[208:209]
	global_load_dwordx4 v[216:219], v[208:209], off
	v_add_u32_e32 v210, s6, v160
	v_ashrrev_i32_e32 v211, 31, v210
	v_lshlrev_b64 v[210:211], 12, v[210:211]
	v_lshl_add_u64 v[210:211], v[6:7], 0, v[210:211]
	global_load_dwordx4 v[220:223], v[210:211], off
	v_add_u32_e32 v0, v38, v157
	v_add_u32_e32 v8, 0x1040, v0
	s_movk_i32 s82, 0x1bff
	s_mov_b64 s[26:27], -1
	s_waitcnt vmcnt(3)
	ds_write2_b32 v0, v2, v3 offset1:1
	ds_write2_b32 v0, v4, v5 offset0:2 offset1:3
	s_waitcnt vmcnt(2)
	ds_write2_b32 v8, v212, v213 offset1:1
	v_add_u32_e32 v2, 0x1048, v0
	ds_write2_b32 v2, v214, v215 offset1:1
	v_add_u32_e32 v8, 0x2080, v0
	s_waitcnt vmcnt(1)
	ds_write2_b32 v8, v216, v217 offset1:1
	v_add_u32_e32 v2, 0x2088, v0
	ds_write2_b32 v2, v218, v219 offset1:1
	s_lshl_b32 s6, s6, 1
	v_add_u32_e32 v6, 0x30c0, v0
	v_add_u32_e32 v0, 0x30c8, v0
	s_add_u32 s24, s21, s6
	s_addc_u32 s25, s35, 0
	s_waitcnt vmcnt(0)
	ds_write2_b32 v6, v220, v221 offset1:1
	ds_write2_b32 v0, v222, v223 offset1:1
	s_waitcnt lgkmcnt(0)
	s_barrier
	s_cbranch_execz .LBB0_298
	s_branch .LBB0_317

.LBB0_318:
	s_and_b32 s4, s5, 0xffff
	s_mul_i32 s4, s4, 0xaaab
	s_lshr_b32 s6, s4, 21
	s_lshr_b32 s4, s4, 15
	s_mul_i32 s6, s6, 48
	s_and_b32 s8, s4, 0xffc0
	s_sub_i32 s4, s5, s6
	s_lshl_b32 s4, s4, 6
	s_and_b32 s4, s4, 0xffc0
	s_lshl_b32 s92, s4, 2
	v_lshl_add_u64 v[6:7], v[42:43], 0, s[92:93]
	v_add_u32_e32 v0, s8, v35
	v_mad_i64_i32 v[2:3], s[6:7], v0, s33, v[6:7]
	s_waitcnt lgkmcnt(0)
	s_barrier
	global_load_dwordx4 v[2:5], v[2:3], off
	v_add_u32_e32 v224, s8, v158
	v_mad_i64_i32 v[206:207], s[6:7], v224, s33, v[6:7]
	global_load_dwordx4 v[212:215], v[206:207], off
	v_add_u32_e32 v224, s8, v159
	v_mad_i64_i32 v[208:209], s[6:7], v224, s33, v[6:7]
	global_load_dwordx4 v[216:219], v[208:209], off
	v_add_u32_e32 v224, s8, v160
	v_mad_i64_i32 v[210:211], s[6:7], v224, s33, v[6:7]
	global_load_dwordx4 v[220:223], v[210:211], off
	v_add_u32_e32 v0, v38, v157
	v_add_u32_e32 v8, 0x1040, v0
	s_lshl_b32 s5, s8, 1
	s_add_u32 s24, s0, s5
	s_movk_i32 s82, 0x1bff
	s_addc_u32 s25, s1, 0
	s_mov_b64 s[26:27], -1
	s_waitcnt vmcnt(3)
	ds_write2_b32 v0, v2, v3 offset1:1
	ds_write2_b32 v0, v4, v5 offset0:2 offset1:3
	s_waitcnt vmcnt(2)
	ds_write2_b32 v8, v212, v213 offset1:1
	v_add_u32_e32 v2, 0x1048, v0
	ds_write2_b32 v2, v214, v215 offset1:1
	v_add_u32_e32 v8, 0x2080, v0
	s_waitcnt vmcnt(1)
	ds_write2_b32 v8, v216, v217 offset1:1
	v_add_u32_e32 v2, 0x2088, v0
	ds_write2_b32 v2, v218, v219 offset1:1
	v_add_u32_e32 v6, 0x30c0, v0
	v_add_u32_e32 v0, 0x30c8, v0
	s_waitcnt vmcnt(0)
	ds_write2_b32 v6, v220, v221 offset1:1
	ds_write2_b32 v0, v222, v223 offset1:1
	s_waitcnt lgkmcnt(0)
	s_barrier
